# FFN-up epilogue: per-tile conv weights staged into spare LDS by LDS-DMA during the main loop (no global loads behind the next-tile prefetch)
# speedup vs baseline: 1.0036x; 1.0036x over previous
; #define PG8_WAIT_V(n) asm volatile("s_waitcnt vmcnt(" #n ")" ::: "memory")
; #define PG8_BAR __builtin_amdgcn_s_barrier()
; __device__ __forceinline__ void conv_epilogue(const GemmDesc& d, const f32x4 (&acc)[2][2][4][2], const Unit& u, int wr, int wc, int fr, int fq, LAS unsigned char* lds) {
;     ...
;         const f32x4 wg0 = *(const f32x4*)(d.R + ch), wg1 = *(const f32x4*)(d.R + 11008 + ch), wg2 = *(const f32x4*)(d.R + 22016 + ch);
;         const f32x4 wu0 = *(const f32x4*)(d.R + DFF + ch), wu1 = *(const f32x4*)(d.R + 11008 + DFF + ch), wu2 = *(const f32x4*)(d.R + 22016 + DFF + ch);
;         const f32x4 bg = *(const f32x4*)(d.rope + ch), bu = *(const f32x4*)(d.rope + DFF + ch);
; __device__ __forceinline__ void gemm_phase(LAS unsigned char* lds, const GemmDesc& g) {
;     ...
;         for (int t = 0; t < nt; t += 2) {
;             const bool last = (t == nt - 2);
;             const char* a1 = cA + (size_t)(t + 1) * kstep;
;             const char* a2 = last ? nA : cA + (size_t)(t + 2) * kstep; const char* b2 = last ? nB : cB + (size_t)(t + 2) * kstep;
;             const char* a3 = a2 + kstep; const char* b3 = b2 + kstep;
;             PG8_LDB(B0, 0, 0); PG8_SCHED; PG8_LDA(At, 0, 0); PG8_STAGE(PG8_SA(1, 1), a1 + hstepA, voffA);
;             PG8_WAIT_L(8); PG8_BAR; PG8_WAIT_L(0); PG8_MMA(0, 0, At, B0); PG8_BAR; PG8_SCHED;
;             PG8_LDB(B1, 0, 1); PG8_STAGE(PG8_SB(0, 0), b2, voffB);
;             PG8_BAR; PG8_WAIT_L(0); PG8_MMA(0, 1, At, B1); PG8_BAR;
;             PG8_LDA(At, 0, 1); PG8_STAGE(PG8_SA(0, 0), a2, voffA);
;             PG8_BAR; PG8_WAIT_L(0); PG8_MMA(1, 0, At, B0); PG8_BAR; PG8_SCHED;
;             PG8_STAGE(PG8_SB(0, 1), b2 + hstep, voffB);
;             PG8_WAIT_V(6); PG8_BAR; PG8_MMA(1, 1, At, B1); PG8_BAR;
;             PG8_LDB(B0, 1, 0); PG8_SCHED; PG8_LDA(At, 1, 0); PG8_STAGE(PG8_SA(0, 1), a2 + hstepA, voffA);
;             PG8_WAIT_L(8); PG8_BAR; PG8_WAIT_L(0); PG8_MMA(0, 0, At, B0); PG8_BAR; PG8_SCHED;
;             PG8_LDB(B1, 1, 1); PG8_STAGE(PG8_SB(1, 0), b3, voffB);
;             PG8_BAR; PG8_WAIT_L(0); PG8_MMA(0, 1, At, B1); PG8_BAR;
;             PG8_LDA(At, 1, 1); PG8_STAGE(PG8_SA(1, 0), a3, voffA);
;             PG8_BAR; PG8_WAIT_L(0); PG8_MMA(1, 0, At, B0); PG8_BAR; PG8_SCHED;
;             PG8_STAGE(PG8_SB(1, 1), b3 + hstep, voffB);
;             PG8_WAIT_V(6); PG8_BAR; PG8_MMA(1, 1, At, B1); PG8_BAR;
.LBB0_208:
	s_cmp_eq_u32 s40, 2
	s_cbranch_scc0 .Lgemm_cw_skip
	v_readlane_b32 s70, v254, 55
	s_nop 3
	s_cmp_lg_u32 s70, 0
	s_cbranch_scc1 .Lgemm_cw_skip
	s_lshr_b32 vcc_lo, s4, 10
	s_cmp_gt_u32 vcc_lo, 3
	s_cbranch_scc1 .Lgemm_cw_skip
	s_mul_i32 vcc_hi, vcc_lo, 0xac00
	s_add_u32 s70, s50, vcc_hi
	s_addc_u32 s71, s51, 0
	s_cmp_eq_u32 vcc_lo, 3
	s_cselect_b32 s70, s58, s70
	s_cselect_b32 s71, s59, s71
	s_lshl_b32 vcc_hi, s9, 9
	s_add_u32 s70, s70, vcc_hi
	s_addc_u32 s71, s71, 0
	v_lshrrev_b32_e32 v194, 5, v215
	v_mul_u32_u24_e32 v194, 0x5600, v194
	v_and_b32_e32 v195, 31, v215
	v_lshl_add_u32 v194, v195, 4, v194
	s_add_i32 m0, s4, 0x20000
	s_nop 0
	global_load_lds_dwordx4 v194, s[70:71]
.Lgemm_cw_skip:
	s_add_i32 s44, s40, 2
	s_add_u32 s42, s0, 0x80
	s_addc_u32 s41, s1, 0
	s_add_i32 s45, 0, 0x10000
	v_add_u32_e32 v144, s45, v200
	ds_read_b128 v[132:135], v144
	ds_read_b128 v[136:139], v144 offset:1024
	ds_read_b128 v[140:143], v144 offset:2048
	ds_read_b128 v[144:147], v144 offset:3072
	s_cmp_eq_u32 s63, s40
	s_cselect_b32 s40, s24, s42
	s_cselect_b32 s41, s25, s41
	s_cselect_b32 s43, s35, s18
	s_cselect_b32 s42, s34, s13
	v_lshl_add_u64 v[194:195], s[0:1], 0, v[174:175]
	s_add_i32 m0, s5, 0xc000
	ds_read_b128 v[148:151], v229
	ds_read_b128 v[152:155], v229 offset:1024
	ds_read_b128 v[156:159], v229 offset:2048
	ds_read_b128 v[160:163], v229 offset:3072
	ds_read_b128 v[178:181], v229 offset:4096
	ds_read_b128 v[182:185], v229 offset:5120
	ds_read_b128 v[186:189], v229 offset:6144
	ds_read_b128 v[190:193], v229 offset:7168
	global_load_lds_dwordx4 v[194:195], off
	v_lshl_add_u64 v[194:195], s[0:1], 0, v[176:177]
	s_add_i32 m0, s5, 0xe000
	s_nop 0
	global_load_lds_dwordx4 v[194:195], off
	s_waitcnt lgkmcnt(8)
	s_barrier
	s_waitcnt lgkmcnt(0)
	s_waitcnt lgkmcnt(0)
	v_mfma_f32_16x16x32_bf16 v[128:131], v[132:135], v[148:151], v[128:131]
	v_mfma_f32_16x16x32_bf16 v[64:67], v[140:143], v[148:151], v[64:67]
	v_mfma_f32_16x16x32_bf16 v[120:123], v[132:135], v[156:159], v[120:123]
	v_mfma_f32_16x16x32_bf16 v[56:59], v[140:143], v[156:159], v[56:59]
	v_mfma_f32_16x16x32_bf16 v[112:115], v[132:135], v[178:181], v[112:115]
	v_mfma_f32_16x16x32_bf16 v[48:51], v[140:143], v[178:181], v[48:51]
	v_mfma_f32_16x16x32_bf16 v[104:107], v[132:135], v[186:189], v[104:107]
	v_mfma_f32_16x16x32_bf16 v[40:43], v[140:143], v[186:189], v[40:43]
	v_mfma_f32_16x16x32_bf16 v[128:131], v[136:139], v[152:155], v[128:131]
	v_mfma_f32_16x16x32_bf16 v[64:67], v[144:147], v[152:155], v[64:67]
	v_mfma_f32_16x16x32_bf16 v[120:123], v[136:139], v[160:163], v[120:123]
	v_mfma_f32_16x16x32_bf16 v[56:59], v[144:147], v[160:163], v[56:59]
	v_mfma_f32_16x16x32_bf16 v[112:115], v[136:139], v[182:185], v[112:115]
	v_mfma_f32_16x16x32_bf16 v[48:51], v[144:147], v[182:185], v[48:51]
	v_mfma_f32_16x16x32_bf16 v[104:107], v[136:139], v[190:193], v[104:107]
	v_mfma_f32_16x16x32_bf16 v[40:43], v[144:147], v[190:193], v[40:43]
	s_barrier
	s_add_i32 vcc_lo, 0, 0x14000
	s_add_i32 s45, s45, s4
	v_add_u32_e32 v220, vcc_lo, v200
	v_lshl_add_u64 v[242:243], s[42:43], 0, v[2:3]
	s_mov_b32 m0, s45
	ds_read_b128 v[194:197], v220
	ds_read_b128 v[230:233], v220 offset:1024
	ds_read_b128 v[234:237], v220 offset:2048
	ds_read_b128 v[238:241], v220 offset:3072
	global_load_lds_dwordx4 v[242:243], off
	v_lshl_add_u64 v[244:245], s[42:43], 0, v[164:165]
	s_add_i32 m0, s45, 0x2000
	s_nop 0
	global_load_lds_dwordx4 v[244:245], off
	s_barrier
	s_waitcnt lgkmcnt(0)
	s_waitcnt lgkmcnt(0)
	v_mfma_f32_16x16x32_bf16 v[124:127], v[194:197], v[148:151], v[124:127]
	v_mfma_f32_16x16x32_bf16 v[60:63], v[234:237], v[148:151], v[60:63]
	v_mfma_f32_16x16x32_bf16 v[116:119], v[194:197], v[156:159], v[116:119]
	v_mfma_f32_16x16x32_bf16 v[52:55], v[234:237], v[156:159], v[52:55]
	v_mfma_f32_16x16x32_bf16 v[108:111], v[194:197], v[178:181], v[108:111]
	v_mfma_f32_16x16x32_bf16 v[44:47], v[234:237], v[178:181], v[44:47]
	v_mfma_f32_16x16x32_bf16 v[100:103], v[194:197], v[186:189], v[100:103]
	v_mfma_f32_16x16x32_bf16 v[36:39], v[234:237], v[186:189], v[36:39]
	v_mfma_f32_16x16x32_bf16 v[124:127], v[230:233], v[152:155], v[124:127]
	v_mfma_f32_16x16x32_bf16 v[60:63], v[238:241], v[152:155], v[60:63]
	v_mfma_f32_16x16x32_bf16 v[116:119], v[230:233], v[160:163], v[116:119]
	v_mfma_f32_16x16x32_bf16 v[52:55], v[238:241], v[160:163], v[52:55]
	v_mfma_f32_16x16x32_bf16 v[108:111], v[230:233], v[182:185], v[108:111]
	v_mfma_f32_16x16x32_bf16 v[44:47], v[238:241], v[182:185], v[44:47]
	v_mfma_f32_16x16x32_bf16 v[100:103], v[230:233], v[190:193], v[100:103]
	v_mfma_f32_16x16x32_bf16 v[36:39], v[238:241], v[190:193], v[36:39]
	s_mov_b32 m0, s5
	v_lshl_add_u64 v[246:247], s[40:41], 0, v[166:167]
	s_barrier
	ds_read_b128 v[148:151], v229 offset:16384
	ds_read_b128 v[152:155], v229 offset:17408
	ds_read_b128 v[156:159], v229 offset:18432
	ds_read_b128 v[160:163], v229 offset:19456
	ds_read_b128 v[178:181], v229 offset:20480
	ds_read_b128 v[182:185], v229 offset:21504
	ds_read_b128 v[186:189], v229 offset:22528
	ds_read_b128 v[190:193], v229 offset:23552
	global_load_lds_dwordx4 v[246:247], off
	v_lshl_add_u64 v[248:249], s[40:41], 0, v[0:1]
	s_mov_b32 m0, s94
	s_nop 0
	global_load_lds_dwordx4 v[248:249], off
	s_barrier
; #define PG8_STAGE(bufoff, gbase, voff) do { _Pragma("unroll") for (int _i = 0; _i < 2; ++_i) \
;         __builtin_amdgcn_global_load_lds((const unsigned*)((const char*)(gbase) + (voff)[_i]), (LAS unsigned*)(lds + (bufoff) + ldsw + _i * 8192), 16, 0, 0); } while (0)
; #define PG8_LDA(dst, b, h) do { _Pragma("unroll") for (int m = 0; m < 4; ++m) _Pragma("unroll") for (int k = 0; k < 2; ++k) dst[m][k] = *(const LAS bf16x8*)(lds + PG8_SA(b, h) + aoff + m * 2048 + k * 1024); } while (0)
; #define PG8_LDB(dst, b, h) do { _Pragma("unroll") for (int n = 0; n < 2; ++n) _Pragma("unroll") for (int k = 0; k < 2; ++k) dst[n][k] = *(const LAS bf16x8*)(lds + PG8_SB(b, h) + boff + n * 2048 + k * 1024); } while (0)
; __device__ __forceinline__ void gemm_phase(LAS unsigned char* lds, const GemmDesc& g) {
;     ...
;         for (int t = 0; t < nt; t += 2) {
;             const bool last = (t == nt - 2);
;             const char* a1 = cA + (size_t)(t + 1) * kstep;
;             const char* a2 = last ? nA : cA + (size_t)(t + 2) * kstep; const char* b2 = last ? nB : cB + (size_t)(t + 2) * kstep;
;             const char* a3 = a2 + kstep; const char* b3 = b2 + kstep;
;             PG8_LDB(B0, 0, 0); PG8_SCHED; PG8_LDA(At, 0, 0); PG8_STAGE(PG8_SA(1, 1), a1 + hstepA, voffA);
;             PG8_WAIT_L(8); PG8_BAR; PG8_WAIT_L(0); PG8_MMA(0, 0, At, B0); PG8_BAR; PG8_SCHED;
;             PG8_LDB(B1, 0, 1); PG8_STAGE(PG8_SB(0, 0), b2, voffB);
;             PG8_BAR; PG8_WAIT_L(0); PG8_MMA(0, 1, At, B1); PG8_BAR;
;             PG8_LDA(At, 0, 1); PG8_STAGE(PG8_SA(0, 0), a2, voffA);
;             PG8_BAR; PG8_WAIT_L(0); PG8_MMA(1, 0, At, B0); PG8_BAR; PG8_SCHED;
;             PG8_STAGE(PG8_SB(0, 1), b2 + hstep, voffB);
;             PG8_WAIT_V(6); PG8_BAR; PG8_MMA(1, 1, At, B1); PG8_BAR;
;             PG8_LDB(B0, 1, 0); PG8_SCHED; PG8_LDA(At, 1, 0); PG8_STAGE(PG8_SA(0, 1), a2 + hstepA, voffA);
;             PG8_WAIT_L(8); PG8_BAR; PG8_WAIT_L(0); PG8_MMA(0, 0, At, B0); PG8_BAR; PG8_SCHED;
;             PG8_LDB(B1, 1, 1); PG8_STAGE(PG8_SB(1, 0), b3, voffB);
;             PG8_BAR; PG8_WAIT_L(0); PG8_MMA(0, 1, At, B1); PG8_BAR;
;             PG8_LDA(At, 1, 1); PG8_STAGE(PG8_SA(1, 0), a3, voffA);
;             PG8_BAR; PG8_WAIT_L(0); PG8_MMA(1, 0, At, B0); PG8_BAR; PG8_SCHED;
;             PG8_STAGE(PG8_SB(1, 1), b3 + hstep, voffB);
;             PG8_WAIT_V(6); PG8_BAR; PG8_MMA(1, 1, At, B1); PG8_BAR;
	s_waitcnt lgkmcnt(0)
	s_waitcnt lgkmcnt(0)
	v_mfma_f32_16x16x32_bf16 v[96:99], v[132:135], v[148:151], v[96:99]
	v_mfma_f32_16x16x32_bf16 v[32:35], v[140:143], v[148:151], v[32:35]
	v_mfma_f32_16x16x32_bf16 v[88:91], v[132:135], v[156:159], v[88:91]
	v_mfma_f32_16x16x32_bf16 v[24:27], v[140:143], v[156:159], v[24:27]
	v_mfma_f32_16x16x32_bf16 v[68:71], v[132:135], v[178:181], v[68:71]
	v_mfma_f32_16x16x32_bf16 v[20:23], v[140:143], v[178:181], v[20:23]
	v_mfma_f32_16x16x32_bf16 v[84:87], v[132:135], v[186:189], v[84:87]
	v_mfma_f32_16x16x32_bf16 v[16:19], v[140:143], v[186:189], v[16:19]
	v_mfma_f32_16x16x32_bf16 v[96:99], v[136:139], v[152:155], v[96:99]
	v_mfma_f32_16x16x32_bf16 v[32:35], v[144:147], v[152:155], v[32:35]
	v_mfma_f32_16x16x32_bf16 v[88:91], v[136:139], v[160:163], v[88:91]
	v_mfma_f32_16x16x32_bf16 v[24:27], v[144:147], v[160:163], v[24:27]
	v_mfma_f32_16x16x32_bf16 v[68:71], v[136:139], v[182:185], v[68:71]
	v_mfma_f32_16x16x32_bf16 v[20:23], v[144:147], v[182:185], v[20:23]
	v_mfma_f32_16x16x32_bf16 v[84:87], v[136:139], v[190:193], v[84:87]
	v_mfma_f32_16x16x32_bf16 v[16:19], v[144:147], v[190:193], v[16:19]
	s_barrier
	s_add_u32 s42, s42, s64
	s_addc_u32 s43, s43, s65
	s_add_i32 s45, vcc_lo, s4
	v_lshl_add_u64 v[220:221], s[42:43], 0, v[2:3]
	s_mov_b32 m0, s45
	v_lshl_add_u64 v[222:223], s[42:43], 0, v[164:165]
	global_load_lds_dwordx4 v[220:221], off
	s_add_i32 m0, s45, 0x2000
	s_nop 0
	global_load_lds_dwordx4 v[222:223], off
	s_waitcnt vmcnt(6)
	s_barrier
	v_mfma_f32_16x16x32_bf16 v[92:95], v[194:197], v[148:151], v[92:95]
	v_mfma_f32_16x16x32_bf16 v[28:31], v[234:237], v[148:151], v[28:31]
	v_mfma_f32_16x16x32_bf16 v[80:83], v[194:197], v[156:159], v[80:83]
	v_mfma_f32_16x16x32_bf16 v[12:15], v[234:237], v[156:159], v[12:15]
	v_mfma_f32_16x16x32_bf16 v[76:79], v[194:197], v[178:181], v[76:79]
	v_mfma_f32_16x16x32_bf16 v[8:11], v[234:237], v[178:181], v[8:11]
	v_mfma_f32_16x16x32_bf16 v[72:75], v[194:197], v[186:189], v[72:75]
	v_mfma_f32_16x16x32_bf16 v[4:7], v[234:237], v[186:189], v[4:7]
	v_mfma_f32_16x16x32_bf16 v[92:95], v[230:233], v[152:155], v[92:95]
	v_mfma_f32_16x16x32_bf16 v[28:31], v[238:241], v[152:155], v[28:31]
	v_mfma_f32_16x16x32_bf16 v[80:83], v[230:233], v[160:163], v[80:83]
	v_mfma_f32_16x16x32_bf16 v[12:15], v[238:241], v[160:163], v[12:15]
	v_mfma_f32_16x16x32_bf16 v[76:79], v[230:233], v[182:185], v[76:79]
	v_mfma_f32_16x16x32_bf16 v[8:11], v[238:241], v[182:185], v[8:11]
	v_mfma_f32_16x16x32_bf16 v[72:75], v[230:233], v[190:193], v[72:75]
	v_mfma_f32_16x16x32_bf16 v[4:7], v[238:241], v[190:193], v[4:7]
	s_add_i32 s42, 0, 0x18000
	v_add_u32_e32 v144, s42, v200
	s_barrier
	ds_read_b128 v[132:135], v144
	ds_read_b128 v[136:139], v144 offset:1024
	ds_read_b128 v[140:143], v144 offset:2048
	ds_read_b128 v[144:147], v144 offset:3072
	s_add_u32 s40, s40, s68
	s_addc_u32 s41, s41, s69
	s_add_i32 m0, s5, 0x4000
	v_lshl_add_u64 v[194:195], s[40:41], 0, v[166:167]
	ds_read_b128 v[148:151], v229 offset:32768
	ds_read_b128 v[152:155], v229 offset:33792
	ds_read_b128 v[156:159], v229 offset:34816
	ds_read_b128 v[160:163], v229 offset:35840
	ds_read_b128 v[178:181], v229 offset:36864
	ds_read_b128 v[182:185], v229 offset:37888
	ds_read_b128 v[186:189], v229 offset:38912
	ds_read_b128 v[190:193], v229 offset:39936
	global_load_lds_dwordx4 v[194:195], off
	v_lshl_add_u64 v[194:195], s[40:41], 0, v[0:1]
	s_add_i32 m0, s5, 0x6000
	s_nop 0
	global_load_lds_dwordx4 v[194:195], off
	s_waitcnt lgkmcnt(8)
	s_barrier
	s_waitcnt lgkmcnt(0)
	s_waitcnt lgkmcnt(0)
	v_mfma_f32_16x16x32_bf16 v[128:131], v[132:135], v[148:151], v[128:131]
	v_mfma_f32_16x16x32_bf16 v[64:67], v[140:143], v[148:151], v[64:67]
	v_mfma_f32_16x16x32_bf16 v[120:123], v[132:135], v[156:159], v[120:123]
	v_mfma_f32_16x16x32_bf16 v[56:59], v[140:143], v[156:159], v[56:59]
	v_mfma_f32_16x16x32_bf16 v[112:115], v[132:135], v[178:181], v[112:115]
	v_mfma_f32_16x16x32_bf16 v[48:51], v[140:143], v[178:181], v[48:51]
	v_mfma_f32_16x16x32_bf16 v[104:107], v[132:135], v[186:189], v[104:107]
	v_mfma_f32_16x16x32_bf16 v[40:43], v[140:143], v[186:189], v[40:43]
	v_mfma_f32_16x16x32_bf16 v[128:131], v[136:139], v[152:155], v[128:131]
	v_mfma_f32_16x16x32_bf16 v[64:67], v[144:147], v[152:155], v[64:67]
	v_mfma_f32_16x16x32_bf16 v[120:123], v[136:139], v[160:163], v[120:123]
	v_mfma_f32_16x16x32_bf16 v[56:59], v[144:147], v[160:163], v[56:59]
	v_mfma_f32_16x16x32_bf16 v[112:115], v[136:139], v[182:185], v[112:115]
	v_mfma_f32_16x16x32_bf16 v[48:51], v[144:147], v[182:185], v[48:51]
	v_mfma_f32_16x16x32_bf16 v[104:107], v[136:139], v[190:193], v[104:107]
	v_mfma_f32_16x16x32_bf16 v[40:43], v[144:147], v[190:193], v[40:43]
	s_barrier
; #define PG8_STAGE(bufoff, gbase, voff) do { _Pragma("unroll") for (int _i = 0; _i < 2; ++_i) \
;         __builtin_amdgcn_global_load_lds((const unsigned*)((const char*)(gbase) + (voff)[_i]), (LAS unsigned*)(lds + (bufoff) + ldsw + _i * 8192), 16, 0, 0); } while (0)
; #define PG8_LDA(dst, b, h) do { _Pragma("unroll") for (int m = 0; m < 4; ++m) _Pragma("unroll") for (int k = 0; k < 2; ++k) dst[m][k] = *(const LAS bf16x8*)(lds + PG8_SA(b, h) + aoff + m * 2048 + k * 1024); } while (0)
; #define PG8_LDB(dst, b, h) do { _Pragma("unroll") for (int n = 0; n < 2; ++n) _Pragma("unroll") for (int k = 0; k < 2; ++k) dst[n][k] = *(const LAS bf16x8*)(lds + PG8_SB(b, h) + boff + n * 2048 + k * 1024); } while (0)
; #define PG8_MMA(ai, bj, At, Bt) do { __builtin_amdgcn_s_setprio(1); _Pragma("unroll") for (int m = 0; m < 4; ++m) _Pragma("unroll") for (int n = 0; n < 2; ++n) _Pragma("unroll") for (int k = 0; k < 2; ++k) \
;         acc[ai][bj][m][n] = __builtin_amdgcn_mfma_f32_16x16x32_bf16(Bt[n][k], At[m][k], acc[ai][bj][m][n], 0, 0, 0); __builtin_amdgcn_s_setprio(0); } while (0)
; #define PG8_WAIT_V(n) asm volatile("s_waitcnt vmcnt(" #n ")" ::: "memory")
; #define PG8_WAIT_L(n) asm volatile("s_waitcnt lgkmcnt(" #n ")" ::: "memory")
; #define PG8_BAR __builtin_amdgcn_s_barrier()
; #define PG8_SCHED __builtin_amdgcn_sched_barrier(0)
; __device__ __forceinline__ void gemm_phase(LAS unsigned char* lds, const GemmDesc& g) {
;     ...
;             PG8_LDB(B0, 1, 0); PG8_SCHED; PG8_LDA(At, 1, 0); PG8_STAGE(PG8_SA(0, 1), a2 + hstepA, voffA);
;             PG8_WAIT_L(8); PG8_BAR; PG8_WAIT_L(0); PG8_MMA(0, 0, At, B0); PG8_BAR; PG8_SCHED;
;             PG8_LDB(B1, 1, 1); PG8_STAGE(PG8_SB(1, 0), b3, voffB);
;             PG8_BAR; PG8_WAIT_L(0); PG8_MMA(0, 1, At, B1); PG8_BAR;
;             PG8_LDA(At, 1, 1); PG8_STAGE(PG8_SA(1, 0), a3, voffA);
;             PG8_BAR; PG8_WAIT_L(0); PG8_MMA(1, 0, At, B0); PG8_BAR; PG8_SCHED;
;             PG8_STAGE(PG8_SB(1, 1), b3 + hstep, voffB);
;             PG8_WAIT_V(6); PG8_BAR; PG8_MMA(1, 1, At, B1); PG8_BAR;
	s_add_i32 s40, 0, 0x1c000
	s_add_i32 s41, s42, s4
	v_add_u32_e32 v238, s40, v200
	v_lshl_add_u64 v[242:243], v[242:243], 0, s[20:21]
	s_mov_b32 m0, s41
	ds_read_b128 v[194:197], v238
	ds_read_b128 v[230:233], v238 offset:1024
	ds_read_b128 v[234:237], v238 offset:2048
	ds_read_b128 v[238:241], v238 offset:3072
	global_load_lds_dwordx4 v[242:243], off
	v_lshl_add_u64 v[242:243], v[244:245], 0, s[20:21]
	s_add_i32 m0, s41, 0x2000
	s_nop 0
	global_load_lds_dwordx4 v[242:243], off
	s_barrier
	s_waitcnt lgkmcnt(0)
	s_waitcnt lgkmcnt(0)
	v_mfma_f32_16x16x32_bf16 v[124:127], v[194:197], v[148:151], v[124:127]
	v_mfma_f32_16x16x32_bf16 v[60:63], v[234:237], v[148:151], v[60:63]
	v_mfma_f32_16x16x32_bf16 v[116:119], v[194:197], v[156:159], v[116:119]
	v_mfma_f32_16x16x32_bf16 v[52:55], v[234:237], v[156:159], v[52:55]
	v_mfma_f32_16x16x32_bf16 v[108:111], v[194:197], v[178:181], v[108:111]
	v_mfma_f32_16x16x32_bf16 v[44:47], v[234:237], v[178:181], v[44:47]
	v_mfma_f32_16x16x32_bf16 v[100:103], v[194:197], v[186:189], v[100:103]
	v_mfma_f32_16x16x32_bf16 v[36:39], v[234:237], v[186:189], v[36:39]
	v_mfma_f32_16x16x32_bf16 v[124:127], v[230:233], v[152:155], v[124:127]
	v_mfma_f32_16x16x32_bf16 v[60:63], v[238:241], v[152:155], v[60:63]
	v_mfma_f32_16x16x32_bf16 v[116:119], v[230:233], v[160:163], v[116:119]
	v_mfma_f32_16x16x32_bf16 v[52:55], v[238:241], v[160:163], v[52:55]
	v_mfma_f32_16x16x32_bf16 v[108:111], v[230:233], v[182:185], v[108:111]
	v_mfma_f32_16x16x32_bf16 v[44:47], v[238:241], v[182:185], v[44:47]
	v_mfma_f32_16x16x32_bf16 v[100:103], v[230:233], v[190:193], v[100:103]
	v_mfma_f32_16x16x32_bf16 v[36:39], v[238:241], v[190:193], v[36:39]
	s_mov_b32 m0, s49
	v_lshl_add_u64 v[242:243], v[246:247], 0, s[20:21]
	s_barrier
	ds_read_b128 v[148:151], v229 offset:49152
	ds_read_b128 v[152:155], v229 offset:50176
	ds_read_b128 v[156:159], v229 offset:51200
	ds_read_b128 v[160:163], v229 offset:52224
	ds_read_b128 v[178:181], v229 offset:53248
	ds_read_b128 v[182:185], v229 offset:54272
	ds_read_b128 v[186:189], v229 offset:55296
	ds_read_b128 v[190:193], v229 offset:56320
	global_load_lds_dwordx4 v[242:243], off
	v_lshl_add_u64 v[242:243], v[248:249], 0, s[20:21]
	s_mov_b32 m0, s62
	s_nop 0
	global_load_lds_dwordx4 v[242:243], off
	s_barrier
	s_waitcnt lgkmcnt(0)
	s_waitcnt lgkmcnt(0)
	v_mfma_f32_16x16x32_bf16 v[96:99], v[132:135], v[148:151], v[96:99]
	v_mfma_f32_16x16x32_bf16 v[32:35], v[140:143], v[148:151], v[32:35]
	v_mfma_f32_16x16x32_bf16 v[88:91], v[132:135], v[156:159], v[88:91]
	v_mfma_f32_16x16x32_bf16 v[24:27], v[140:143], v[156:159], v[24:27]
	v_mfma_f32_16x16x32_bf16 v[68:71], v[132:135], v[178:181], v[68:71]
	v_mfma_f32_16x16x32_bf16 v[20:23], v[140:143], v[178:181], v[20:23]
	v_mfma_f32_16x16x32_bf16 v[84:87], v[132:135], v[186:189], v[84:87]
	v_mfma_f32_16x16x32_bf16 v[16:19], v[140:143], v[186:189], v[16:19]
	v_mfma_f32_16x16x32_bf16 v[96:99], v[136:139], v[152:155], v[96:99]
	v_mfma_f32_16x16x32_bf16 v[32:35], v[144:147], v[152:155], v[32:35]
	v_mfma_f32_16x16x32_bf16 v[88:91], v[136:139], v[160:163], v[88:91]
	v_mfma_f32_16x16x32_bf16 v[24:27], v[144:147], v[160:163], v[24:27]
	v_mfma_f32_16x16x32_bf16 v[68:71], v[136:139], v[182:185], v[68:71]
	v_mfma_f32_16x16x32_bf16 v[20:23], v[144:147], v[182:185], v[20:23]
	v_mfma_f32_16x16x32_bf16 v[84:87], v[136:139], v[190:193], v[84:87]
	v_mfma_f32_16x16x32_bf16 v[16:19], v[144:147], v[190:193], v[16:19]
	s_barrier
	s_add_i32 s40, s40, s4
	v_lshl_add_u64 v[132:133], v[220:221], 0, s[20:21]
	s_mov_b32 m0, s40
	s_nop 0
	global_load_lds_dwordx4 v[132:133], off
	v_lshl_add_u64 v[132:133], v[222:223], 0, s[20:21]
	s_add_i32 m0, s40, 0x2000
	s_nop 0
	global_load_lds_dwordx4 v[132:133], off
	s_waitcnt vmcnt(6)
	s_barrier
	v_mfma_f32_16x16x32_bf16 v[92:95], v[194:197], v[148:151], v[92:95]
	v_mfma_f32_16x16x32_bf16 v[28:31], v[234:237], v[148:151], v[28:31]
	v_mfma_f32_16x16x32_bf16 v[80:83], v[194:197], v[156:159], v[80:83]
	v_mfma_f32_16x16x32_bf16 v[12:15], v[234:237], v[156:159], v[12:15]
	v_mfma_f32_16x16x32_bf16 v[76:79], v[194:197], v[178:181], v[76:79]
	v_mfma_f32_16x16x32_bf16 v[8:11], v[234:237], v[178:181], v[8:11]
	v_mfma_f32_16x16x32_bf16 v[72:75], v[194:197], v[186:189], v[72:75]
	v_mfma_f32_16x16x32_bf16 v[4:7], v[234:237], v[186:189], v[4:7]
	v_mfma_f32_16x16x32_bf16 v[92:95], v[230:233], v[152:155], v[92:95]
	v_mfma_f32_16x16x32_bf16 v[28:31], v[238:241], v[152:155], v[28:31]
	v_mfma_f32_16x16x32_bf16 v[80:83], v[230:233], v[160:163], v[80:83]
	v_mfma_f32_16x16x32_bf16 v[12:15], v[238:241], v[160:163], v[12:15]
	v_mfma_f32_16x16x32_bf16 v[76:79], v[230:233], v[182:185], v[76:79]
	v_mfma_f32_16x16x32_bf16 v[8:11], v[238:241], v[182:185], v[8:11]
	v_mfma_f32_16x16x32_bf16 v[72:75], v[230:233], v[190:193], v[72:75]
	v_mfma_f32_16x16x32_bf16 v[4:7], v[238:241], v[190:193], v[4:7]
	s_add_u32 s0, s0, 0x100
	s_addc_u32 s1, s1, 0
	s_add_u32 s13, s13, 0x100
	s_addc_u32 s18, s18, 0
	s_cmp_ge_u32 s44, s48
	s_mov_b32 s40, s44
	s_barrier
	s_cbranch_scc0 .LBB0_208
	s_branch .LBB0_214

; #define LAS __attribute__((address_space(3)))
; __device__ __forceinline__ float silu_f(float v) { return v / (1.0f + fexp2(-v * LOG2E)); }
; __device__ __forceinline__ void conv_epilogue(const GemmDesc& d, const f32x4 (&acc)[2][2][4][2], const Unit& u, int wr, int wc, int fr, int fq, LAS unsigned char* lds) {
;     const int L = 16 * wr + fr;
;     const bool seq_start = (u.pm & 15) == 0;
;     const int ch0 = u.pn * 128 + wc * 32 + fq * 8;
;     if (fr == 0 || fr == 15) {
;         const int rbase = (fr == 0) ? 4 * wr : 4 * wr + 2;
; #pragma unroll
;         for (int e2 = 0; e2 < 2; ++e2)
; #pragma unroll
;             for (int bj = 0; bj < 2; ++bj)
; #pragma unroll
;                 for (int n = 0; n < 2; ++n) {
;                     const f32x4 v = (fr == 0) ? acc[0][bj][e2][n] : acc[1][bj][2 + e2][n];
;                     *(f32x4*)(d.aux + ((size_t)((u.pm * 8 + rbase + e2) * 2 + bj)) * DFF + ch0 + 4 * n) = v;
;                 }
;     }
;     bf16_t* gout = (bf16_t*)d.C;
; #pragma unroll
;     for (int n = 0; n < 2; ++n) {
;         const int ch = ch0 + 4 * n;
;         const f32x4 wg0 = *(const f32x4*)(d.R + ch), wg1 = *(const f32x4*)(d.R + 11008 + ch), wg2 = *(const f32x4*)(d.R + 22016 + ch);
;         const f32x4 wu0 = *(const f32x4*)(d.R + DFF + ch), wu1 = *(const f32x4*)(d.R + 11008 + DFF + ch), wu2 = *(const f32x4*)(d.R + 22016 + DFF + ch);
;         const f32x4 bg = *(const f32x4*)(d.rope + ch), bu = *(const f32x4*)(d.rope + DFF + ch);
;         f32x4 pg2 = dpp_prev(acc[1][0][2][n]), pg1 = dpp_prev(acc[1][0][3][n]), pu2 = dpp_prev(acc[1][1][2][n]), pu1 = dpp_prev(acc[1][1][3][n]);
;         if (fr == 0) { pg2 = (f32x4){0.f, 0.f, 0.f, 0.f}; pg1 = pg2; pu2 = pg2; pu1 = pg2; }
; #pragma unroll
;         for (int e = 0; e < 8; ++e) {
;             const f32x4 cg_ = acc[e >> 2][0][e & 3][n], cu_ = acc[e >> 2][1][e & 3][n];
;             const f32x4 yg = bg + wg0 * pg2 + wg1 * pg1 + wg2 * cg_;
;             const f32x4 yu = bu + wu0 * pu2 + wu1 * pu1 + wu2 * cu_;
;             f32x4 r;
; #pragma unroll
;             for (int j = 0; j < 4; ++j) r[j] = silu_f(yg[j]) * yu[j];
;             u32x2 pk; pk.x = cvt_pk_bf16(r[0], r[1]); pk.y = cvt_pk_bf16(r[2], r[3]);
;             { const bool skip = (fr == 0) && (e < 2) && !(wr == 0 && seq_start);
;               if (!skip) *(u32x2*)(gout + (size_t)(u.pm * 256 + 8 * L + e) * DFF + ch) = pk; }
.LBB0_368:
	s_and_b64 vcc, exec, s[0:1]
	s_cbranch_vccz .LBB0_194
	v_lshl_or_b32 v169, s9, 7, v211
	v_lshlrev_b32_e32 v170, 2, v169
	v_lshlrev_b32_e32 v171, 2, v211
	v_add_u32_e32 v171, 0x20000, v171
	ds_read_b128 v[132:135], v171 offset:0
	ds_read_b128 v[136:139], v171 offset:1024
	ds_read_b128 v[140:143], v171 offset:2048
	ds_read_b128 v[144:147], v171 offset:512
	ds_read_b128 v[148:151], v171 offset:1536
	ds_read_b128 v[152:155], v171 offset:2560
	ds_read_b128 v[156:159], v171 offset:3072
	ds_read_b128 v[160:163], v171 offset:3584
	ds_read_b128 v[178:181], v171 offset:16
	ds_read_b128 v[182:185], v171 offset:1040
	ds_read_b128 v[186:189], v171 offset:2064
	ds_read_b128 v[190:193], v171 offset:528
	ds_read_b128 v[194:197], v171 offset:1552
	ds_read_b128 v[230:233], v171 offset:2576
	ds_read_b128 v[234:237], v171 offset:3088
	ds_read_b128 v[238:241], v171 offset:3600
	v_readlane_b32 s40, v254, 47
	v_readlane_b32 s41, v254, 48
	s_lshl_b32 s13, s11, 4
	v_add_u32_e32 v171, s13, v201
	s_movk_i32 s13, 0x5600
	v_mad_u32_u24 v168, v171, s13, v170
	v_cmp_eq_u32_e64 s[0:1], 15, v198
	s_nop 1
	s_or_b64 s[0:1], s[0:1], s[38:39]
	s_and_saveexec_b64 s[44:45], s[0:1]
	v_cndmask_b32_e64 v242, v68, v128, s[38:39]
	v_cndmask_b32_e64 v243, v69, v129, s[38:39]
	v_cndmask_b32_e64 v244, v70, v130, s[38:39]
	v_cndmask_b32_e64 v245, v71, v131, s[38:39]
	global_store_dwordx4 v168, v[242:245], s[40:41]
	v_cndmask_b32_e64 v246, v20, v64, s[38:39]
	v_cndmask_b32_e64 v247, v21, v65, s[38:39]
	v_cndmask_b32_e64 v248, v22, v66, s[38:39]
	v_cndmask_b32_e64 v249, v23, v67, s[38:39]
	global_store_dwordx4 v168, v[246:249], s[40:41] offset:16
	v_add_u32_e32 v168, 0x5600, v168
	v_cndmask_b32_e64 v242, v76, v124, s[38:39]
	v_cndmask_b32_e64 v243, v77, v125, s[38:39]
	v_cndmask_b32_e64 v244, v78, v126, s[38:39]
	v_cndmask_b32_e64 v245, v79, v127, s[38:39]
	global_store_dwordx4 v168, v[242:245], s[40:41]
	v_cndmask_b32_e64 v246, v8, v60, s[38:39]
	v_cndmask_b32_e64 v247, v9, v61, s[38:39]
	v_cndmask_b32_e64 v248, v10, v62, s[38:39]
	v_cndmask_b32_e64 v249, v11, v63, s[38:39]
	global_store_dwordx4 v168, v[246:249], s[40:41] offset:16
	v_add_u32_e32 v168, 0x5600, v168
	v_cndmask_b32_e64 v242, v84, v120, s[38:39]
	v_cndmask_b32_e64 v243, v85, v121, s[38:39]
	v_cndmask_b32_e64 v244, v86, v122, s[38:39]
	v_cndmask_b32_e64 v245, v87, v123, s[38:39]
	global_store_dwordx4 v168, v[242:245], s[40:41]
	v_cndmask_b32_e64 v246, v16, v56, s[38:39]
	v_cndmask_b32_e64 v247, v17, v57, s[38:39]
	v_cndmask_b32_e64 v248, v18, v58, s[38:39]
	v_cndmask_b32_e64 v249, v19, v59, s[38:39]
	global_store_dwordx4 v168, v[246:249], s[40:41] offset:16
	v_add_u32_e32 v168, 0x5600, v168
	v_cndmask_b32_e64 v242, v72, v116, s[38:39]
	v_cndmask_b32_e64 v243, v73, v117, s[38:39]
	v_cndmask_b32_e64 v244, v74, v118, s[38:39]
	v_cndmask_b32_e64 v245, v75, v119, s[38:39]
	global_store_dwordx4 v168, v[242:245], s[40:41]
	v_cndmask_b32_e64 v246, v4, v52, s[38:39]
	v_cndmask_b32_e64 v247, v5, v53, s[38:39]
	v_cndmask_b32_e64 v248, v6, v54, s[38:39]
	v_cndmask_b32_e64 v249, v7, v55, s[38:39]
	global_store_dwordx4 v168, v[246:249], s[40:41] offset:16
	s_mov_b64 exec, s[44:45]
	s_lshl_b32 s13, s11, 8
	v_add_u32_e32 v171, s13, v203
	s_movk_i32 s13, 0x2b00
	v_mul_u32_u24_e32 v168, s13, v171
	v_lshl_add_u32 v168, v169, 1, v168
	s_and_b32 s0, s11, 15
	s_cmp_lg_u32 s0, 0
	s_cselect_b64 s[0:1], -1, 0
	v_readlane_b32 s42, v254, 59
	v_readlane_b32 s43, v254, 60
	s_nop 1
	s_or_b64 s[0:1], s[42:43], s[0:1]
	s_and_b64 s[0:1], s[0:1], s[38:39]
	s_andn2_b64 s[42:43], exec, s[0:1]
	s_waitcnt lgkmcnt(0)
	v_mov_b32_e32 v242, v156
	v_mov_b32_e32 v243, v157
	v_mov_b32_e32 v244, v158
	v_mov_b32_e32 v245, v159
	v_fmac_f32_dpp v242, v68, v132 row_shr:1 row_mask:0xf bank_mask:0xf bound_ctrl:1
	v_fmac_f32_dpp v243, v69, v133 row_shr:1 row_mask:0xf bank_mask:0xf bound_ctrl:1
	v_fmac_f32_dpp v244, v70, v134 row_shr:1 row_mask:0xf bank_mask:0xf bound_ctrl:1
	v_fmac_f32_dpp v245, v71, v135 row_shr:1 row_mask:0xf bank_mask:0xf bound_ctrl:1
	v_fmac_f32_dpp v242, v84, v136 row_shr:1 row_mask:0xf bank_mask:0xf bound_ctrl:1
	v_fmac_f32_dpp v243, v85, v137 row_shr:1 row_mask:0xf bank_mask:0xf bound_ctrl:1
	v_fmac_f32_dpp v244, v86, v138 row_shr:1 row_mask:0xf bank_mask:0xf bound_ctrl:1
	v_fmac_f32_dpp v245, v87, v139 row_shr:1 row_mask:0xf bank_mask:0xf bound_ctrl:1
	v_pk_fma_f32 v[242:243], v[140:141], v[128:129], v[242:243]
	v_pk_fma_f32 v[244:245], v[142:143], v[130:131], v[244:245]
	v_mul_f32_e32 v246, 0xbfb8aa3b, v242
	v_mul_f32_e32 v247, 0xbfb8aa3b, v243
	v_mul_f32_e32 v248, 0xbfb8aa3b, v244
	v_mul_f32_e32 v249, 0xbfb8aa3b, v245
	v_exp_f32_e32 v246, v246
	v_exp_f32_e32 v247, v247
	v_exp_f32_e32 v248, v248
	v_exp_f32_e32 v249, v249
	s_nop 0
	v_pk_add_f32 v[246:247], v[246:247], 1.0 op_sel_hi:[1,0]
	v_pk_add_f32 v[248:249], v[248:249], 1.0 op_sel_hi:[1,0]
	v_rcp_f32_e32 v246, v246
	v_rcp_f32_e32 v247, v247
	v_rcp_f32_e32 v248, v248
	v_rcp_f32_e32 v249, v249
	s_nop 0
	v_pk_mul_f32 v[242:243], v[242:243], v[246:247]
	v_pk_mul_f32 v[244:245], v[244:245], v[248:249]
	v_mov_b32_e32 v246, v160
	v_mov_b32_e32 v247, v161
	v_mov_b32_e32 v248, v162
	v_mov_b32_e32 v249, v163
	v_fmac_f32_dpp v246, v76, v144 row_shr:1 row_mask:0xf bank_mask:0xf bound_ctrl:1
	v_fmac_f32_dpp v247, v77, v145 row_shr:1 row_mask:0xf bank_mask:0xf bound_ctrl:1
	v_fmac_f32_dpp v248, v78, v146 row_shr:1 row_mask:0xf bank_mask:0xf bound_ctrl:1
	v_fmac_f32_dpp v249, v79, v147 row_shr:1 row_mask:0xf bank_mask:0xf bound_ctrl:1
	v_fmac_f32_dpp v246, v72, v148 row_shr:1 row_mask:0xf bank_mask:0xf bound_ctrl:1
	v_fmac_f32_dpp v247, v73, v149 row_shr:1 row_mask:0xf bank_mask:0xf bound_ctrl:1
; __device__ __forceinline__ unsigned cvt_pk_bf16(float lo, float hi) { const f32x2v v = {lo, hi}; const b16x2v r = __builtin_convertvector(v, b16x2v); return __builtin_bit_cast(unsigned, r); }
; __device__ __forceinline__ float silu_f(float v) { return v / (1.0f + fexp2(-v * LOG2E)); }
; __device__ __forceinline__ void conv_epilogue(const GemmDesc& d, const f32x4 (&acc)[2][2][4][2], const Unit& u, int wr, int wc, int fr, int fq, LAS unsigned char* lds) {
;     ...
; #pragma unroll
;         for (int e = 0; e < 8; ++e) {
;             const f32x4 cg_ = acc[e >> 2][0][e & 3][n], cu_ = acc[e >> 2][1][e & 3][n];
;             const f32x4 yg = bg + wg0 * pg2 + wg1 * pg1 + wg2 * cg_;
;             const f32x4 yu = bu + wu0 * pu2 + wu1 * pu1 + wu2 * cu_;
;             f32x4 r;
; #pragma unroll
;             for (int j = 0; j < 4; ++j) r[j] = silu_f(yg[j]) * yu[j];
;             u32x2 pk; pk.x = cvt_pk_bf16(r[0], r[1]); pk.y = cvt_pk_bf16(r[2], r[3]);
;             { const bool skip = (fr == 0) && (e < 2) && !(wr == 0 && seq_start);
;               if (!skip) *(u32x2*)(gout + (size_t)(u.pm * 256 + 8 * L + e) * DFF + ch) = pk; }
;             pg2 = pg1; pg1 = cg_; pu2 = pu1; pu1 = cu_;
;         }
	v_fmac_f32_dpp v248, v74, v150 row_shr:1 row_mask:0xf bank_mask:0xf bound_ctrl:1
	v_fmac_f32_dpp v249, v75, v151 row_shr:1 row_mask:0xf bank_mask:0xf bound_ctrl:1
	v_pk_fma_f32 v[246:247], v[152:153], v[124:125], v[246:247]
	v_pk_fma_f32 v[248:249], v[154:155], v[126:127], v[248:249]
	v_pk_mul_f32 v[242:243], v[246:247], v[242:243]
	v_pk_mul_f32 v[244:245], v[248:249], v[244:245]
	v_cvt_pk_bf16_f32 v220, v242, v243
	v_cvt_pk_bf16_f32 v221, v244, v245
	v_mov_b32_e32 v242, v234
	v_mov_b32_e32 v243, v235
	v_mov_b32_e32 v244, v236
	v_mov_b32_e32 v245, v237
	v_fmac_f32_dpp v242, v20, v178 row_shr:1 row_mask:0xf bank_mask:0xf bound_ctrl:1
	v_fmac_f32_dpp v243, v21, v179 row_shr:1 row_mask:0xf bank_mask:0xf bound_ctrl:1
	v_fmac_f32_dpp v244, v22, v180 row_shr:1 row_mask:0xf bank_mask:0xf bound_ctrl:1
	v_fmac_f32_dpp v245, v23, v181 row_shr:1 row_mask:0xf bank_mask:0xf bound_ctrl:1
	v_fmac_f32_dpp v242, v16, v182 row_shr:1 row_mask:0xf bank_mask:0xf bound_ctrl:1
	v_fmac_f32_dpp v243, v17, v183 row_shr:1 row_mask:0xf bank_mask:0xf bound_ctrl:1
	v_fmac_f32_dpp v244, v18, v184 row_shr:1 row_mask:0xf bank_mask:0xf bound_ctrl:1
	v_fmac_f32_dpp v245, v19, v185 row_shr:1 row_mask:0xf bank_mask:0xf bound_ctrl:1
	v_pk_fma_f32 v[242:243], v[186:187], v[64:65], v[242:243]
	v_pk_fma_f32 v[244:245], v[188:189], v[66:67], v[244:245]
	v_mul_f32_e32 v246, 0xbfb8aa3b, v242
	v_mul_f32_e32 v247, 0xbfb8aa3b, v243
	v_mul_f32_e32 v248, 0xbfb8aa3b, v244
	v_mul_f32_e32 v249, 0xbfb8aa3b, v245
	v_exp_f32_e32 v246, v246
	v_exp_f32_e32 v247, v247
	v_exp_f32_e32 v248, v248
	v_exp_f32_e32 v249, v249
	s_nop 0
	v_pk_add_f32 v[246:247], v[246:247], 1.0 op_sel_hi:[1,0]
	v_pk_add_f32 v[248:249], v[248:249], 1.0 op_sel_hi:[1,0]
	v_rcp_f32_e32 v246, v246
	v_rcp_f32_e32 v247, v247
	v_rcp_f32_e32 v248, v248
	v_rcp_f32_e32 v249, v249
	s_nop 0
	v_pk_mul_f32 v[242:243], v[242:243], v[246:247]
	v_pk_mul_f32 v[244:245], v[244:245], v[248:249]
	v_mov_b32_e32 v246, v238
	v_mov_b32_e32 v247, v239
	v_mov_b32_e32 v248, v240
	v_mov_b32_e32 v249, v241
	v_fmac_f32_dpp v246, v8, v190 row_shr:1 row_mask:0xf bank_mask:0xf bound_ctrl:1
	v_fmac_f32_dpp v247, v9, v191 row_shr:1 row_mask:0xf bank_mask:0xf bound_ctrl:1
	v_fmac_f32_dpp v248, v10, v192 row_shr:1 row_mask:0xf bank_mask:0xf bound_ctrl:1
	v_fmac_f32_dpp v249, v11, v193 row_shr:1 row_mask:0xf bank_mask:0xf bound_ctrl:1
	v_fmac_f32_dpp v246, v4, v194 row_shr:1 row_mask:0xf bank_mask:0xf bound_ctrl:1
	v_fmac_f32_dpp v247, v5, v195 row_shr:1 row_mask:0xf bank_mask:0xf bound_ctrl:1
	v_fmac_f32_dpp v248, v6, v196 row_shr:1 row_mask:0xf bank_mask:0xf bound_ctrl:1
	v_fmac_f32_dpp v249, v7, v197 row_shr:1 row_mask:0xf bank_mask:0xf bound_ctrl:1
	v_pk_fma_f32 v[246:247], v[230:231], v[60:61], v[246:247]
	v_pk_fma_f32 v[248:249], v[232:233], v[62:63], v[248:249]
	v_pk_mul_f32 v[242:243], v[246:247], v[242:243]
	v_pk_mul_f32 v[244:245], v[248:249], v[244:245]
	v_cvt_pk_bf16_f32 v222, v242, v243
	v_cvt_pk_bf16_f32 v223, v244, v245
	s_mov_b64 s[44:45], exec
	s_mov_b64 exec, s[42:43]
	global_store_dwordx4 v168, v[220:223], s[2:3]
	s_mov_b64 exec, s[44:45]
	v_add_u32_e32 v168, 0x2b00, v168
	v_mov_b32_e32 v242, v156
	v_mov_b32_e32 v243, v157
	v_mov_b32_e32 v244, v158
	v_mov_b32_e32 v245, v159
	v_fmac_f32_dpp v242, v84, v132 row_shr:1 row_mask:0xf bank_mask:0xf bound_ctrl:1
	v_fmac_f32_dpp v243, v85, v133 row_shr:1 row_mask:0xf bank_mask:0xf bound_ctrl:1
	v_fmac_f32_dpp v244, v86, v134 row_shr:1 row_mask:0xf bank_mask:0xf bound_ctrl:1
	v_fmac_f32_dpp v245, v87, v135 row_shr:1 row_mask:0xf bank_mask:0xf bound_ctrl:1
	v_pk_fma_f32 v[242:243], v[136:137], v[128:129], v[242:243]
	v_pk_fma_f32 v[244:245], v[138:139], v[130:131], v[244:245]
	v_pk_fma_f32 v[242:243], v[140:141], v[120:121], v[242:243]
	v_pk_fma_f32 v[244:245], v[142:143], v[122:123], v[244:245]
	v_mul_f32_e32 v246, 0xbfb8aa3b, v242
	v_mul_f32_e32 v247, 0xbfb8aa3b, v243
	v_mul_f32_e32 v248, 0xbfb8aa3b, v244
	v_mul_f32_e32 v249, 0xbfb8aa3b, v245
	v_exp_f32_e32 v246, v246
	v_exp_f32_e32 v247, v247
	v_exp_f32_e32 v248, v248
	v_exp_f32_e32 v249, v249
	s_nop 0
	v_pk_add_f32 v[246:247], v[246:247], 1.0 op_sel_hi:[1,0]
	v_pk_add_f32 v[248:249], v[248:249], 1.0 op_sel_hi:[1,0]
	v_rcp_f32_e32 v246, v246
	v_rcp_f32_e32 v247, v247
	v_rcp_f32_e32 v248, v248
	v_rcp_f32_e32 v249, v249
	s_nop 0
	v_pk_mul_f32 v[242:243], v[242:243], v[246:247]
	v_pk_mul_f32 v[244:245], v[244:245], v[248:249]
	v_mov_b32_e32 v246, v160
	v_mov_b32_e32 v247, v161
	v_mov_b32_e32 v248, v162
	v_mov_b32_e32 v249, v163
	v_fmac_f32_dpp v246, v72, v144 row_shr:1 row_mask:0xf bank_mask:0xf bound_ctrl:1
	v_fmac_f32_dpp v247, v73, v145 row_shr:1 row_mask:0xf bank_mask:0xf bound_ctrl:1
	v_fmac_f32_dpp v248, v74, v146 row_shr:1 row_mask:0xf bank_mask:0xf bound_ctrl:1
	v_fmac_f32_dpp v249, v75, v147 row_shr:1 row_mask:0xf bank_mask:0xf bound_ctrl:1
	v_pk_fma_f32 v[246:247], v[148:149], v[124:125], v[246:247]
	v_pk_fma_f32 v[248:249], v[150:151], v[126:127], v[248:249]
	v_pk_fma_f32 v[246:247], v[152:153], v[116:117], v[246:247]
	v_pk_fma_f32 v[248:249], v[154:155], v[118:119], v[248:249]
	v_pk_mul_f32 v[242:243], v[246:247], v[242:243]
	v_pk_mul_f32 v[244:245], v[248:249], v[244:245]
	v_cvt_pk_bf16_f32 v220, v242, v243
	v_cvt_pk_bf16_f32 v221, v244, v245
	v_mov_b32_e32 v242, v234
	v_mov_b32_e32 v243, v235
	v_mov_b32_e32 v244, v236
	v_mov_b32_e32 v245, v237
	v_fmac_f32_dpp v242, v16, v178 row_shr:1 row_mask:0xf bank_mask:0xf bound_ctrl:1
	v_fmac_f32_dpp v243, v17, v179 row_shr:1 row_mask:0xf bank_mask:0xf bound_ctrl:1
	v_fmac_f32_dpp v244, v18, v180 row_shr:1 row_mask:0xf bank_mask:0xf bound_ctrl:1
	v_fmac_f32_dpp v245, v19, v181 row_shr:1 row_mask:0xf bank_mask:0xf bound_ctrl:1
; __device__ __forceinline__ unsigned cvt_pk_bf16(float lo, float hi) { const f32x2v v = {lo, hi}; const b16x2v r = __builtin_convertvector(v, b16x2v); return __builtin_bit_cast(unsigned, r); }
; __device__ __forceinline__ float silu_f(float v) { return v / (1.0f + fexp2(-v * LOG2E)); }
; __device__ __forceinline__ void conv_epilogue(const GemmDesc& d, const f32x4 (&acc)[2][2][4][2], const Unit& u, int wr, int wc, int fr, int fq, LAS unsigned char* lds) {
;     ...
; #pragma unroll
;         for (int e = 0; e < 8; ++e) {
;             const f32x4 cg_ = acc[e >> 2][0][e & 3][n], cu_ = acc[e >> 2][1][e & 3][n];
;             const f32x4 yg = bg + wg0 * pg2 + wg1 * pg1 + wg2 * cg_;
;             const f32x4 yu = bu + wu0 * pu2 + wu1 * pu1 + wu2 * cu_;
;             f32x4 r;
; #pragma unroll
;             for (int j = 0; j < 4; ++j) r[j] = silu_f(yg[j]) * yu[j];
;             u32x2 pk; pk.x = cvt_pk_bf16(r[0], r[1]); pk.y = cvt_pk_bf16(r[2], r[3]);
;             { const bool skip = (fr == 0) && (e < 2) && !(wr == 0 && seq_start);
;               if (!skip) *(u32x2*)(gout + (size_t)(u.pm * 256 + 8 * L + e) * DFF + ch) = pk; }
;             pg2 = pg1; pg1 = cg_; pu2 = pu1; pu1 = cu_;
;         }
	v_pk_fma_f32 v[242:243], v[182:183], v[64:65], v[242:243]
	v_pk_fma_f32 v[244:245], v[184:185], v[66:67], v[244:245]
	v_pk_fma_f32 v[242:243], v[186:187], v[56:57], v[242:243]
	v_pk_fma_f32 v[244:245], v[188:189], v[58:59], v[244:245]
	v_mul_f32_e32 v246, 0xbfb8aa3b, v242
	v_mul_f32_e32 v247, 0xbfb8aa3b, v243
	v_mul_f32_e32 v248, 0xbfb8aa3b, v244
	v_mul_f32_e32 v249, 0xbfb8aa3b, v245
	v_exp_f32_e32 v246, v246
	v_exp_f32_e32 v247, v247
	v_exp_f32_e32 v248, v248
	v_exp_f32_e32 v249, v249
	s_nop 0
	v_pk_add_f32 v[246:247], v[246:247], 1.0 op_sel_hi:[1,0]
	v_pk_add_f32 v[248:249], v[248:249], 1.0 op_sel_hi:[1,0]
	v_rcp_f32_e32 v246, v246
	v_rcp_f32_e32 v247, v247
	v_rcp_f32_e32 v248, v248
	v_rcp_f32_e32 v249, v249
	s_nop 0
	v_pk_mul_f32 v[242:243], v[242:243], v[246:247]
	v_pk_mul_f32 v[244:245], v[244:245], v[248:249]
	v_mov_b32_e32 v246, v238
	v_mov_b32_e32 v247, v239
	v_mov_b32_e32 v248, v240
	v_mov_b32_e32 v249, v241
	v_fmac_f32_dpp v246, v4, v190 row_shr:1 row_mask:0xf bank_mask:0xf bound_ctrl:1
	v_fmac_f32_dpp v247, v5, v191 row_shr:1 row_mask:0xf bank_mask:0xf bound_ctrl:1
	v_fmac_f32_dpp v248, v6, v192 row_shr:1 row_mask:0xf bank_mask:0xf bound_ctrl:1
	v_fmac_f32_dpp v249, v7, v193 row_shr:1 row_mask:0xf bank_mask:0xf bound_ctrl:1
	v_pk_fma_f32 v[246:247], v[194:195], v[60:61], v[246:247]
	v_pk_fma_f32 v[248:249], v[196:197], v[62:63], v[248:249]
	v_pk_fma_f32 v[246:247], v[230:231], v[52:53], v[246:247]
	v_pk_fma_f32 v[248:249], v[232:233], v[54:55], v[248:249]
	v_pk_mul_f32 v[242:243], v[246:247], v[242:243]
	v_pk_mul_f32 v[244:245], v[248:249], v[244:245]
	v_cvt_pk_bf16_f32 v222, v242, v243
	v_cvt_pk_bf16_f32 v223, v244, v245
	s_mov_b64 s[44:45], exec
	s_mov_b64 exec, s[42:43]
	global_store_dwordx4 v168, v[220:223], s[2:3]
	s_mov_b64 exec, s[44:45]
	v_add_u32_e32 v168, 0x2b00, v168
	v_pk_fma_f32 v[242:243], v[132:133], v[128:129], v[156:157]
	v_pk_fma_f32 v[244:245], v[134:135], v[130:131], v[158:159]
	v_pk_fma_f32 v[242:243], v[136:137], v[120:121], v[242:243]
	v_pk_fma_f32 v[244:245], v[138:139], v[122:123], v[244:245]
	v_pk_fma_f32 v[242:243], v[140:141], v[112:113], v[242:243]
	v_pk_fma_f32 v[244:245], v[142:143], v[114:115], v[244:245]
	v_mul_f32_e32 v246, 0xbfb8aa3b, v242
	v_mul_f32_e32 v247, 0xbfb8aa3b, v243
	v_mul_f32_e32 v248, 0xbfb8aa3b, v244
	v_mul_f32_e32 v249, 0xbfb8aa3b, v245
	v_exp_f32_e32 v246, v246
	v_exp_f32_e32 v247, v247
	v_exp_f32_e32 v248, v248
	v_exp_f32_e32 v249, v249
	s_nop 0
	v_pk_add_f32 v[246:247], v[246:247], 1.0 op_sel_hi:[1,0]
	v_pk_add_f32 v[248:249], v[248:249], 1.0 op_sel_hi:[1,0]
	v_rcp_f32_e32 v246, v246
	v_rcp_f32_e32 v247, v247
	v_rcp_f32_e32 v248, v248
	v_rcp_f32_e32 v249, v249
	s_nop 0
	v_pk_mul_f32 v[242:243], v[242:243], v[246:247]
	v_pk_mul_f32 v[244:245], v[244:245], v[248:249]
	v_pk_fma_f32 v[246:247], v[144:145], v[124:125], v[160:161]
	v_pk_fma_f32 v[248:249], v[146:147], v[126:127], v[162:163]
	v_pk_fma_f32 v[246:247], v[148:149], v[116:117], v[246:247]
	v_pk_fma_f32 v[248:249], v[150:151], v[118:119], v[248:249]
	v_pk_fma_f32 v[246:247], v[152:153], v[108:109], v[246:247]
	v_pk_fma_f32 v[248:249], v[154:155], v[110:111], v[248:249]
	v_pk_mul_f32 v[242:243], v[246:247], v[242:243]
	v_pk_mul_f32 v[244:245], v[248:249], v[244:245]
	v_cvt_pk_bf16_f32 v220, v242, v243
	v_cvt_pk_bf16_f32 v221, v244, v245
	v_pk_fma_f32 v[242:243], v[178:179], v[64:65], v[234:235]
	v_pk_fma_f32 v[244:245], v[180:181], v[66:67], v[236:237]
	v_pk_fma_f32 v[242:243], v[182:183], v[56:57], v[242:243]
	v_pk_fma_f32 v[244:245], v[184:185], v[58:59], v[244:245]
	v_pk_fma_f32 v[242:243], v[186:187], v[48:49], v[242:243]
	v_pk_fma_f32 v[244:245], v[188:189], v[50:51], v[244:245]
	v_mul_f32_e32 v246, 0xbfb8aa3b, v242
	v_mul_f32_e32 v247, 0xbfb8aa3b, v243
	v_mul_f32_e32 v248, 0xbfb8aa3b, v244
	v_mul_f32_e32 v249, 0xbfb8aa3b, v245
	v_exp_f32_e32 v246, v246
	v_exp_f32_e32 v247, v247
	v_exp_f32_e32 v248, v248
	v_exp_f32_e32 v249, v249
	s_nop 0
	v_pk_add_f32 v[246:247], v[246:247], 1.0 op_sel_hi:[1,0]
	v_pk_add_f32 v[248:249], v[248:249], 1.0 op_sel_hi:[1,0]
	v_rcp_f32_e32 v246, v246
	v_rcp_f32_e32 v247, v247
	v_rcp_f32_e32 v248, v248
	v_rcp_f32_e32 v249, v249
	s_nop 0
	v_pk_mul_f32 v[242:243], v[242:243], v[246:247]
	v_pk_mul_f32 v[244:245], v[244:245], v[248:249]
	v_pk_fma_f32 v[246:247], v[190:191], v[60:61], v[238:239]
	v_pk_fma_f32 v[248:249], v[192:193], v[62:63], v[240:241]
	v_pk_fma_f32 v[246:247], v[194:195], v[52:53], v[246:247]
	v_pk_fma_f32 v[248:249], v[196:197], v[54:55], v[248:249]
	v_pk_fma_f32 v[246:247], v[230:231], v[44:45], v[246:247]
	v_pk_fma_f32 v[248:249], v[232:233], v[46:47], v[248:249]
	v_pk_mul_f32 v[242:243], v[246:247], v[242:243]
	v_pk_mul_f32 v[244:245], v[248:249], v[244:245]
	v_cvt_pk_bf16_f32 v222, v242, v243
	v_cvt_pk_bf16_f32 v223, v244, v245
	global_store_dwordx4 v168, v[220:223], s[2:3]
	v_add_u32_e32 v168, 0x2b00, v168
	v_pk_fma_f32 v[242:243], v[132:133], v[120:121], v[156:157]
	v_pk_fma_f32 v[244:245], v[134:135], v[122:123], v[158:159]
	v_pk_fma_f32 v[242:243], v[136:137], v[112:113], v[242:243]
	v_pk_fma_f32 v[244:245], v[138:139], v[114:115], v[244:245]
	v_pk_fma_f32 v[242:243], v[140:141], v[104:105], v[242:243]
	v_pk_fma_f32 v[244:245], v[142:143], v[106:107], v[244:245]
	v_mul_f32_e32 v246, 0xbfb8aa3b, v242
	v_mul_f32_e32 v247, 0xbfb8aa3b, v243
	v_mul_f32_e32 v248, 0xbfb8aa3b, v244
	v_mul_f32_e32 v249, 0xbfb8aa3b, v245
	v_exp_f32_e32 v246, v246
	v_exp_f32_e32 v247, v247
	v_exp_f32_e32 v248, v248
	v_exp_f32_e32 v249, v249
	s_nop 0
	v_pk_add_f32 v[246:247], v[246:247], 1.0 op_sel_hi:[1,0]
	v_pk_add_f32 v[248:249], v[248:249], 1.0 op_sel_hi:[1,0]
	v_rcp_f32_e32 v246, v246
; __device__ __forceinline__ unsigned cvt_pk_bf16(float lo, float hi) { const f32x2v v = {lo, hi}; const b16x2v r = __builtin_convertvector(v, b16x2v); return __builtin_bit_cast(unsigned, r); }
; __device__ __forceinline__ float silu_f(float v) { return v / (1.0f + fexp2(-v * LOG2E)); }
; __device__ __forceinline__ void conv_epilogue(const GemmDesc& d, const f32x4 (&acc)[2][2][4][2], const Unit& u, int wr, int wc, int fr, int fq, LAS unsigned char* lds) {
;     ...
; #pragma unroll
;         for (int e = 0; e < 8; ++e) {
;             const f32x4 cg_ = acc[e >> 2][0][e & 3][n], cu_ = acc[e >> 2][1][e & 3][n];
;             const f32x4 yg = bg + wg0 * pg2 + wg1 * pg1 + wg2 * cg_;
;             const f32x4 yu = bu + wu0 * pu2 + wu1 * pu1 + wu2 * cu_;
;             f32x4 r;
; #pragma unroll
;             for (int j = 0; j < 4; ++j) r[j] = silu_f(yg[j]) * yu[j];
;             u32x2 pk; pk.x = cvt_pk_bf16(r[0], r[1]); pk.y = cvt_pk_bf16(r[2], r[3]);
;             { const bool skip = (fr == 0) && (e < 2) && !(wr == 0 && seq_start);
;               if (!skip) *(u32x2*)(gout + (size_t)(u.pm * 256 + 8 * L + e) * DFF + ch) = pk; }
;             pg2 = pg1; pg1 = cg_; pu2 = pu1; pu1 = cu_;
;         }
	v_rcp_f32_e32 v247, v247
	v_rcp_f32_e32 v248, v248
	v_rcp_f32_e32 v249, v249
	s_nop 0
	v_pk_mul_f32 v[242:243], v[242:243], v[246:247]
	v_pk_mul_f32 v[244:245], v[244:245], v[248:249]
	v_pk_fma_f32 v[246:247], v[144:145], v[116:117], v[160:161]
	v_pk_fma_f32 v[248:249], v[146:147], v[118:119], v[162:163]
	v_pk_fma_f32 v[246:247], v[148:149], v[108:109], v[246:247]
	v_pk_fma_f32 v[248:249], v[150:151], v[110:111], v[248:249]
	v_pk_fma_f32 v[246:247], v[152:153], v[100:101], v[246:247]
	v_pk_fma_f32 v[248:249], v[154:155], v[102:103], v[248:249]
	v_pk_mul_f32 v[242:243], v[246:247], v[242:243]
	v_pk_mul_f32 v[244:245], v[248:249], v[244:245]
	v_cvt_pk_bf16_f32 v220, v242, v243
	v_cvt_pk_bf16_f32 v221, v244, v245
	v_pk_fma_f32 v[242:243], v[178:179], v[56:57], v[234:235]
	v_pk_fma_f32 v[244:245], v[180:181], v[58:59], v[236:237]
	v_pk_fma_f32 v[242:243], v[182:183], v[48:49], v[242:243]
	v_pk_fma_f32 v[244:245], v[184:185], v[50:51], v[244:245]
	v_pk_fma_f32 v[242:243], v[186:187], v[40:41], v[242:243]
	v_pk_fma_f32 v[244:245], v[188:189], v[42:43], v[244:245]
	v_mul_f32_e32 v246, 0xbfb8aa3b, v242
	v_mul_f32_e32 v247, 0xbfb8aa3b, v243
	v_mul_f32_e32 v248, 0xbfb8aa3b, v244
	v_mul_f32_e32 v249, 0xbfb8aa3b, v245
	v_exp_f32_e32 v246, v246
	v_exp_f32_e32 v247, v247
	v_exp_f32_e32 v248, v248
	v_exp_f32_e32 v249, v249
	s_nop 0
	v_pk_add_f32 v[246:247], v[246:247], 1.0 op_sel_hi:[1,0]
	v_pk_add_f32 v[248:249], v[248:249], 1.0 op_sel_hi:[1,0]
	v_rcp_f32_e32 v246, v246
	v_rcp_f32_e32 v247, v247
	v_rcp_f32_e32 v248, v248
	v_rcp_f32_e32 v249, v249
	s_nop 0
	v_pk_mul_f32 v[242:243], v[242:243], v[246:247]
	v_pk_mul_f32 v[244:245], v[244:245], v[248:249]
	v_pk_fma_f32 v[246:247], v[190:191], v[52:53], v[238:239]
	v_pk_fma_f32 v[248:249], v[192:193], v[54:55], v[240:241]
	v_pk_fma_f32 v[246:247], v[194:195], v[44:45], v[246:247]
	v_pk_fma_f32 v[248:249], v[196:197], v[46:47], v[248:249]
	v_pk_fma_f32 v[246:247], v[230:231], v[36:37], v[246:247]
	v_pk_fma_f32 v[248:249], v[232:233], v[38:39], v[248:249]
	v_pk_mul_f32 v[242:243], v[246:247], v[242:243]
	v_pk_mul_f32 v[244:245], v[248:249], v[244:245]
	v_cvt_pk_bf16_f32 v222, v242, v243
	v_cvt_pk_bf16_f32 v223, v244, v245
	global_store_dwordx4 v168, v[220:223], s[2:3]
	v_add_u32_e32 v168, 0x2b00, v168
	v_pk_fma_f32 v[242:243], v[132:133], v[112:113], v[156:157]
	v_pk_fma_f32 v[244:245], v[134:135], v[114:115], v[158:159]
	v_pk_fma_f32 v[242:243], v[136:137], v[104:105], v[242:243]
	v_pk_fma_f32 v[244:245], v[138:139], v[106:107], v[244:245]
	v_pk_fma_f32 v[242:243], v[140:141], v[96:97], v[242:243]
	v_pk_fma_f32 v[244:245], v[142:143], v[98:99], v[244:245]
	v_mul_f32_e32 v246, 0xbfb8aa3b, v242
	v_mul_f32_e32 v247, 0xbfb8aa3b, v243
	v_mul_f32_e32 v248, 0xbfb8aa3b, v244
	v_mul_f32_e32 v249, 0xbfb8aa3b, v245
	v_exp_f32_e32 v246, v246
	v_exp_f32_e32 v247, v247
	v_exp_f32_e32 v248, v248
	v_exp_f32_e32 v249, v249
	s_nop 0
	v_pk_add_f32 v[246:247], v[246:247], 1.0 op_sel_hi:[1,0]
	v_pk_add_f32 v[248:249], v[248:249], 1.0 op_sel_hi:[1,0]
	v_rcp_f32_e32 v246, v246
	v_rcp_f32_e32 v247, v247
	v_rcp_f32_e32 v248, v248
	v_rcp_f32_e32 v249, v249
	s_nop 0
	v_pk_mul_f32 v[242:243], v[242:243], v[246:247]
	v_pk_mul_f32 v[244:245], v[244:245], v[248:249]
	v_pk_fma_f32 v[246:247], v[144:145], v[108:109], v[160:161]
	v_pk_fma_f32 v[248:249], v[146:147], v[110:111], v[162:163]
	v_pk_fma_f32 v[246:247], v[148:149], v[100:101], v[246:247]
	v_pk_fma_f32 v[248:249], v[150:151], v[102:103], v[248:249]
	v_pk_fma_f32 v[246:247], v[152:153], v[92:93], v[246:247]
	v_pk_fma_f32 v[248:249], v[154:155], v[94:95], v[248:249]
	v_pk_mul_f32 v[242:243], v[246:247], v[242:243]
	v_pk_mul_f32 v[244:245], v[248:249], v[244:245]
	v_cvt_pk_bf16_f32 v220, v242, v243
	v_cvt_pk_bf16_f32 v221, v244, v245
	v_pk_fma_f32 v[242:243], v[178:179], v[48:49], v[234:235]
	v_pk_fma_f32 v[244:245], v[180:181], v[50:51], v[236:237]
	v_pk_fma_f32 v[242:243], v[182:183], v[40:41], v[242:243]
	v_pk_fma_f32 v[244:245], v[184:185], v[42:43], v[244:245]
	v_pk_fma_f32 v[242:243], v[186:187], v[32:33], v[242:243]
	v_pk_fma_f32 v[244:245], v[188:189], v[34:35], v[244:245]
	v_mul_f32_e32 v246, 0xbfb8aa3b, v242
	v_mul_f32_e32 v247, 0xbfb8aa3b, v243
	v_mul_f32_e32 v248, 0xbfb8aa3b, v244
	v_mul_f32_e32 v249, 0xbfb8aa3b, v245
	v_exp_f32_e32 v246, v246
	v_exp_f32_e32 v247, v247
	v_exp_f32_e32 v248, v248
	v_exp_f32_e32 v249, v249
	s_nop 0
	v_pk_add_f32 v[246:247], v[246:247], 1.0 op_sel_hi:[1,0]
	v_pk_add_f32 v[248:249], v[248:249], 1.0 op_sel_hi:[1,0]
	v_rcp_f32_e32 v246, v246
	v_rcp_f32_e32 v247, v247
	v_rcp_f32_e32 v248, v248
	v_rcp_f32_e32 v249, v249
	s_nop 0
	v_pk_mul_f32 v[242:243], v[242:243], v[246:247]
	v_pk_mul_f32 v[244:245], v[244:245], v[248:249]
	v_pk_fma_f32 v[246:247], v[190:191], v[44:45], v[238:239]
	v_pk_fma_f32 v[248:249], v[192:193], v[46:47], v[240:241]
	v_pk_fma_f32 v[246:247], v[194:195], v[36:37], v[246:247]
	v_pk_fma_f32 v[248:249], v[196:197], v[38:39], v[248:249]
	v_pk_fma_f32 v[246:247], v[230:231], v[28:29], v[246:247]
	v_pk_fma_f32 v[248:249], v[232:233], v[30:31], v[248:249]
	v_pk_mul_f32 v[242:243], v[246:247], v[242:243]
	v_pk_mul_f32 v[244:245], v[248:249], v[244:245]
	v_cvt_pk_bf16_f32 v222, v242, v243
	v_cvt_pk_bf16_f32 v223, v244, v245
	global_store_dwordx4 v168, v[220:223], s[2:3]
	v_add_u32_e32 v168, 0x2b00, v168
	v_pk_fma_f32 v[242:243], v[132:133], v[104:105], v[156:157]
	v_pk_fma_f32 v[244:245], v[134:135], v[106:107], v[158:159]
	v_pk_fma_f32 v[242:243], v[136:137], v[96:97], v[242:243]
	v_pk_fma_f32 v[244:245], v[138:139], v[98:99], v[244:245]
	v_pk_fma_f32 v[242:243], v[140:141], v[88:89], v[242:243]
	v_pk_fma_f32 v[244:245], v[142:143], v[90:91], v[244:245]
; __device__ __forceinline__ unsigned cvt_pk_bf16(float lo, float hi) { const f32x2v v = {lo, hi}; const b16x2v r = __builtin_convertvector(v, b16x2v); return __builtin_bit_cast(unsigned, r); }
; __device__ __forceinline__ float silu_f(float v) { return v / (1.0f + fexp2(-v * LOG2E)); }
; __device__ __forceinline__ void conv_epilogue(const GemmDesc& d, const f32x4 (&acc)[2][2][4][2], const Unit& u, int wr, int wc, int fr, int fq, LAS unsigned char* lds) {
;     ...
; #pragma unroll
;         for (int e = 0; e < 8; ++e) {
;             const f32x4 cg_ = acc[e >> 2][0][e & 3][n], cu_ = acc[e >> 2][1][e & 3][n];
;             const f32x4 yg = bg + wg0 * pg2 + wg1 * pg1 + wg2 * cg_;
;             const f32x4 yu = bu + wu0 * pu2 + wu1 * pu1 + wu2 * cu_;
;             f32x4 r;
; #pragma unroll
;             for (int j = 0; j < 4; ++j) r[j] = silu_f(yg[j]) * yu[j];
;             u32x2 pk; pk.x = cvt_pk_bf16(r[0], r[1]); pk.y = cvt_pk_bf16(r[2], r[3]);
;             { const bool skip = (fr == 0) && (e < 2) && !(wr == 0 && seq_start);
;               if (!skip) *(u32x2*)(gout + (size_t)(u.pm * 256 + 8 * L + e) * DFF + ch) = pk; }
;             pg2 = pg1; pg1 = cg_; pu2 = pu1; pu1 = cu_;
;         }
	v_mul_f32_e32 v246, 0xbfb8aa3b, v242
	v_mul_f32_e32 v247, 0xbfb8aa3b, v243
	v_mul_f32_e32 v248, 0xbfb8aa3b, v244
	v_mul_f32_e32 v249, 0xbfb8aa3b, v245
	v_exp_f32_e32 v246, v246
	v_exp_f32_e32 v247, v247
	v_exp_f32_e32 v248, v248
	v_exp_f32_e32 v249, v249
	s_nop 0
	v_pk_add_f32 v[246:247], v[246:247], 1.0 op_sel_hi:[1,0]
	v_pk_add_f32 v[248:249], v[248:249], 1.0 op_sel_hi:[1,0]
	v_rcp_f32_e32 v246, v246
	v_rcp_f32_e32 v247, v247
	v_rcp_f32_e32 v248, v248
	v_rcp_f32_e32 v249, v249
	s_nop 0
	v_pk_mul_f32 v[242:243], v[242:243], v[246:247]
	v_pk_mul_f32 v[244:245], v[244:245], v[248:249]
	v_pk_fma_f32 v[246:247], v[144:145], v[100:101], v[160:161]
	v_pk_fma_f32 v[248:249], v[146:147], v[102:103], v[162:163]
	v_pk_fma_f32 v[246:247], v[148:149], v[92:93], v[246:247]
	v_pk_fma_f32 v[248:249], v[150:151], v[94:95], v[248:249]
	v_pk_fma_f32 v[246:247], v[152:153], v[80:81], v[246:247]
	v_pk_fma_f32 v[248:249], v[154:155], v[82:83], v[248:249]
	v_pk_mul_f32 v[242:243], v[246:247], v[242:243]
	v_pk_mul_f32 v[244:245], v[248:249], v[244:245]
	v_cvt_pk_bf16_f32 v220, v242, v243
	v_cvt_pk_bf16_f32 v221, v244, v245
	v_pk_fma_f32 v[242:243], v[178:179], v[40:41], v[234:235]
	v_pk_fma_f32 v[244:245], v[180:181], v[42:43], v[236:237]
	v_pk_fma_f32 v[242:243], v[182:183], v[32:33], v[242:243]
	v_pk_fma_f32 v[244:245], v[184:185], v[34:35], v[244:245]
	v_pk_fma_f32 v[242:243], v[186:187], v[24:25], v[242:243]
	v_pk_fma_f32 v[244:245], v[188:189], v[26:27], v[244:245]
	v_mul_f32_e32 v246, 0xbfb8aa3b, v242
	v_mul_f32_e32 v247, 0xbfb8aa3b, v243
	v_mul_f32_e32 v248, 0xbfb8aa3b, v244
	v_mul_f32_e32 v249, 0xbfb8aa3b, v245
	v_exp_f32_e32 v246, v246
	v_exp_f32_e32 v247, v247
	v_exp_f32_e32 v248, v248
	v_exp_f32_e32 v249, v249
	s_nop 0
	v_pk_add_f32 v[246:247], v[246:247], 1.0 op_sel_hi:[1,0]
	v_pk_add_f32 v[248:249], v[248:249], 1.0 op_sel_hi:[1,0]
	v_rcp_f32_e32 v246, v246
	v_rcp_f32_e32 v247, v247
	v_rcp_f32_e32 v248, v248
	v_rcp_f32_e32 v249, v249
	s_nop 0
	v_pk_mul_f32 v[242:243], v[242:243], v[246:247]
	v_pk_mul_f32 v[244:245], v[244:245], v[248:249]
	v_pk_fma_f32 v[246:247], v[190:191], v[36:37], v[238:239]
	v_pk_fma_f32 v[248:249], v[192:193], v[38:39], v[240:241]
	v_pk_fma_f32 v[246:247], v[194:195], v[28:29], v[246:247]
	v_pk_fma_f32 v[248:249], v[196:197], v[30:31], v[248:249]
	v_pk_fma_f32 v[246:247], v[230:231], v[12:13], v[246:247]
	v_pk_fma_f32 v[248:249], v[232:233], v[14:15], v[248:249]
	v_pk_mul_f32 v[242:243], v[246:247], v[242:243]
	v_pk_mul_f32 v[244:245], v[248:249], v[244:245]
	v_cvt_pk_bf16_f32 v222, v242, v243
	v_cvt_pk_bf16_f32 v223, v244, v245
	global_store_dwordx4 v168, v[220:223], s[2:3]
	v_add_u32_e32 v168, 0x2b00, v168
	v_pk_fma_f32 v[242:243], v[132:133], v[96:97], v[156:157]
	v_pk_fma_f32 v[244:245], v[134:135], v[98:99], v[158:159]
	v_pk_fma_f32 v[242:243], v[136:137], v[88:89], v[242:243]
	v_pk_fma_f32 v[244:245], v[138:139], v[90:91], v[244:245]
	v_pk_fma_f32 v[242:243], v[140:141], v[68:69], v[242:243]
	v_pk_fma_f32 v[244:245], v[142:143], v[70:71], v[244:245]
	v_mul_f32_e32 v246, 0xbfb8aa3b, v242
	v_mul_f32_e32 v247, 0xbfb8aa3b, v243
	v_mul_f32_e32 v248, 0xbfb8aa3b, v244
	v_mul_f32_e32 v249, 0xbfb8aa3b, v245
	v_exp_f32_e32 v246, v246
	v_exp_f32_e32 v247, v247
	v_exp_f32_e32 v248, v248
	v_exp_f32_e32 v249, v249
	s_nop 0
	v_pk_add_f32 v[246:247], v[246:247], 1.0 op_sel_hi:[1,0]
	v_pk_add_f32 v[248:249], v[248:249], 1.0 op_sel_hi:[1,0]
	v_rcp_f32_e32 v246, v246
	v_rcp_f32_e32 v247, v247
	v_rcp_f32_e32 v248, v248
	v_rcp_f32_e32 v249, v249
	s_nop 0
	v_pk_mul_f32 v[242:243], v[242:243], v[246:247]
	v_pk_mul_f32 v[244:245], v[244:245], v[248:249]
	v_pk_fma_f32 v[246:247], v[144:145], v[92:93], v[160:161]
	v_pk_fma_f32 v[248:249], v[146:147], v[94:95], v[162:163]
	v_pk_fma_f32 v[246:247], v[148:149], v[80:81], v[246:247]
	v_pk_fma_f32 v[248:249], v[150:151], v[82:83], v[248:249]
	v_pk_fma_f32 v[246:247], v[152:153], v[76:77], v[246:247]
	v_pk_fma_f32 v[248:249], v[154:155], v[78:79], v[248:249]
	v_pk_mul_f32 v[242:243], v[246:247], v[242:243]
	v_pk_mul_f32 v[244:245], v[248:249], v[244:245]
	v_cvt_pk_bf16_f32 v220, v242, v243
	v_cvt_pk_bf16_f32 v221, v244, v245
	v_pk_fma_f32 v[242:243], v[178:179], v[32:33], v[234:235]
	v_pk_fma_f32 v[244:245], v[180:181], v[34:35], v[236:237]
	v_pk_fma_f32 v[242:243], v[182:183], v[24:25], v[242:243]
; __device__ __forceinline__ unsigned cvt_pk_bf16(float lo, float hi) { const f32x2v v = {lo, hi}; const b16x2v r = __builtin_convertvector(v, b16x2v); return __builtin_bit_cast(unsigned, r); }
; __device__ __forceinline__ float silu_f(float v) { return v / (1.0f + fexp2(-v * LOG2E)); }
; __device__ __forceinline__ void conv_epilogue(const GemmDesc& d, const f32x4 (&acc)[2][2][4][2], const Unit& u, int wr, int wc, int fr, int fq, LAS unsigned char* lds) {
;     ...
; #pragma unroll
;         for (int e = 0; e < 8; ++e) {
;             const f32x4 cg_ = acc[e >> 2][0][e & 3][n], cu_ = acc[e >> 2][1][e & 3][n];
;             const f32x4 yg = bg + wg0 * pg2 + wg1 * pg1 + wg2 * cg_;
;             const f32x4 yu = bu + wu0 * pu2 + wu1 * pu1 + wu2 * cu_;
;             f32x4 r;
; #pragma unroll
;             for (int j = 0; j < 4; ++j) r[j] = silu_f(yg[j]) * yu[j];
;             u32x2 pk; pk.x = cvt_pk_bf16(r[0], r[1]); pk.y = cvt_pk_bf16(r[2], r[3]);
;             { const bool skip = (fr == 0) && (e < 2) && !(wr == 0 && seq_start);
;               if (!skip) *(u32x2*)(gout + (size_t)(u.pm * 256 + 8 * L + e) * DFF + ch) = pk; }
;             pg2 = pg1; pg1 = cg_; pu2 = pu1; pu1 = cu_;
;         }
	v_pk_fma_f32 v[244:245], v[184:185], v[26:27], v[244:245]
	v_pk_fma_f32 v[242:243], v[186:187], v[20:21], v[242:243]
	v_pk_fma_f32 v[244:245], v[188:189], v[22:23], v[244:245]
	v_mul_f32_e32 v246, 0xbfb8aa3b, v242
	v_mul_f32_e32 v247, 0xbfb8aa3b, v243
	v_mul_f32_e32 v248, 0xbfb8aa3b, v244
	v_mul_f32_e32 v249, 0xbfb8aa3b, v245
	v_exp_f32_e32 v246, v246
	v_exp_f32_e32 v247, v247
	v_exp_f32_e32 v248, v248
	v_exp_f32_e32 v249, v249
	s_nop 0
	v_pk_add_f32 v[246:247], v[246:247], 1.0 op_sel_hi:[1,0]
	v_pk_add_f32 v[248:249], v[248:249], 1.0 op_sel_hi:[1,0]
	v_rcp_f32_e32 v246, v246
	v_rcp_f32_e32 v247, v247
	v_rcp_f32_e32 v248, v248
	v_rcp_f32_e32 v249, v249
	s_nop 0
	v_pk_mul_f32 v[242:243], v[242:243], v[246:247]
	v_pk_mul_f32 v[244:245], v[244:245], v[248:249]
	v_pk_fma_f32 v[246:247], v[190:191], v[28:29], v[238:239]
	v_pk_fma_f32 v[248:249], v[192:193], v[30:31], v[240:241]
	v_pk_fma_f32 v[246:247], v[194:195], v[12:13], v[246:247]
	v_pk_fma_f32 v[248:249], v[196:197], v[14:15], v[248:249]
	v_pk_fma_f32 v[246:247], v[230:231], v[8:9], v[246:247]
	v_pk_fma_f32 v[248:249], v[232:233], v[10:11], v[248:249]
	v_pk_mul_f32 v[242:243], v[246:247], v[242:243]
	v_pk_mul_f32 v[244:245], v[248:249], v[244:245]
	v_cvt_pk_bf16_f32 v222, v242, v243
	v_cvt_pk_bf16_f32 v223, v244, v245
	global_store_dwordx4 v168, v[220:223], s[2:3]
	v_add_u32_e32 v168, 0x2b00, v168
	v_pk_fma_f32 v[242:243], v[132:133], v[88:89], v[156:157]
	v_pk_fma_f32 v[244:245], v[134:135], v[90:91], v[158:159]
	v_pk_fma_f32 v[242:243], v[136:137], v[68:69], v[242:243]
	v_pk_fma_f32 v[244:245], v[138:139], v[70:71], v[244:245]
	v_pk_fma_f32 v[242:243], v[140:141], v[84:85], v[242:243]
	v_pk_fma_f32 v[244:245], v[142:143], v[86:87], v[244:245]
	v_mul_f32_e32 v246, 0xbfb8aa3b, v242
	v_mul_f32_e32 v247, 0xbfb8aa3b, v243
	v_mul_f32_e32 v248, 0xbfb8aa3b, v244
	v_mul_f32_e32 v249, 0xbfb8aa3b, v245
	v_exp_f32_e32 v246, v246
	v_exp_f32_e32 v247, v247
	v_exp_f32_e32 v248, v248
	v_exp_f32_e32 v249, v249
	s_nop 0
	v_pk_add_f32 v[246:247], v[246:247], 1.0 op_sel_hi:[1,0]
	v_pk_add_f32 v[248:249], v[248:249], 1.0 op_sel_hi:[1,0]
	v_rcp_f32_e32 v246, v246
	v_rcp_f32_e32 v247, v247
	v_rcp_f32_e32 v248, v248
	v_rcp_f32_e32 v249, v249
	s_nop 0
	v_pk_mul_f32 v[242:243], v[242:243], v[246:247]
	v_pk_mul_f32 v[244:245], v[244:245], v[248:249]
	v_pk_fma_f32 v[246:247], v[144:145], v[80:81], v[160:161]
	v_pk_fma_f32 v[248:249], v[146:147], v[82:83], v[162:163]
	v_pk_fma_f32 v[246:247], v[148:149], v[76:77], v[246:247]
	v_pk_fma_f32 v[248:249], v[150:151], v[78:79], v[248:249]
	v_pk_fma_f32 v[246:247], v[152:153], v[72:73], v[246:247]
	v_pk_fma_f32 v[248:249], v[154:155], v[74:75], v[248:249]
	v_pk_mul_f32 v[242:243], v[246:247], v[242:243]
	v_pk_mul_f32 v[244:245], v[248:249], v[244:245]
	v_cvt_pk_bf16_f32 v220, v242, v243
	v_cvt_pk_bf16_f32 v221, v244, v245
	v_pk_fma_f32 v[242:243], v[178:179], v[24:25], v[234:235]
	v_pk_fma_f32 v[244:245], v[180:181], v[26:27], v[236:237]
	v_pk_fma_f32 v[242:243], v[182:183], v[20:21], v[242:243]
	v_pk_fma_f32 v[244:245], v[184:185], v[22:23], v[244:245]
	v_pk_fma_f32 v[242:243], v[186:187], v[16:17], v[242:243]
	v_pk_fma_f32 v[244:245], v[188:189], v[18:19], v[244:245]
	v_mul_f32_e32 v246, 0xbfb8aa3b, v242
	v_mul_f32_e32 v247, 0xbfb8aa3b, v243
	v_mul_f32_e32 v248, 0xbfb8aa3b, v244
	v_mul_f32_e32 v249, 0xbfb8aa3b, v245
	v_exp_f32_e32 v246, v246
	v_exp_f32_e32 v247, v247
	v_exp_f32_e32 v248, v248
	v_exp_f32_e32 v249, v249
	s_nop 0
	v_pk_add_f32 v[246:247], v[246:247], 1.0 op_sel_hi:[1,0]
	v_pk_add_f32 v[248:249], v[248:249], 1.0 op_sel_hi:[1,0]
	v_rcp_f32_e32 v246, v246
	v_rcp_f32_e32 v247, v247
	v_rcp_f32_e32 v248, v248
	v_rcp_f32_e32 v249, v249
	s_nop 0
	v_pk_mul_f32 v[242:243], v[242:243], v[246:247]
	v_pk_mul_f32 v[244:245], v[244:245], v[248:249]
	v_pk_fma_f32 v[246:247], v[190:191], v[12:13], v[238:239]
	v_pk_fma_f32 v[248:249], v[192:193], v[14:15], v[240:241]
	v_pk_fma_f32 v[246:247], v[194:195], v[8:9], v[246:247]
	v_pk_fma_f32 v[248:249], v[196:197], v[10:11], v[248:249]
	v_pk_fma_f32 v[246:247], v[230:231], v[4:5], v[246:247]
	v_pk_fma_f32 v[248:249], v[232:233], v[6:7], v[248:249]
	v_pk_mul_f32 v[242:243], v[246:247], v[242:243]
	v_pk_mul_f32 v[244:245], v[248:249], v[244:245]
	v_cvt_pk_bf16_f32 v222, v242, v243
	v_cvt_pk_bf16_f32 v223, v244, v245
	global_store_dwordx4 v168, v[220:223], s[2:3]
	s_branch .LBB0_194
